# hidden-activation stores of the swiglu epilogue made write-through (sc1) so the 4 MiB L2 keeps the A/B tiles
# baseline (speedup 1.0000x reference)
.LBB0_531:
	v_lshl_add_u32 v154, s54, 12, v145
	ds_read_b128 v[96:99], v154
	ds_read_b128 v[234:237], v154 offset:256
	s_waitcnt lgkmcnt(1)
	v_mov_b32_e32 v150, v97
	v_mov_b32_e32 v151, v98
	v_mov_b32_e32 v97, v99
	v_pk_add_f32 v[96:97], v[150:151], v[96:97]
	v_lshl_add_u32 v151, s24, 8, v139
	v_add_f32_e32 v96, v96, v97
	v_fmamk_f32 v96, v96, 0x3a800000, v229
	v_rsq_f32_e32 v150, v96
	ds_read_b128 v[96:99], v154 offset:512
	v_pk_mul_f32 v[128:129], v[128:129], v[150:151] op_sel_hi:[1,0]
	v_pk_mul_f32 v[124:125], v[124:125], v[150:151] op_sel_hi:[1,0]
	s_waitcnt lgkmcnt(1)
	v_mov_b32_e32 v152, v235
	v_mov_b32_e32 v153, v236
	v_mov_b32_e32 v235, v237
	v_pk_add_f32 v[234:235], v[152:153], v[234:235]
	v_pk_mul_f32 v[124:125], v[124:125], v[128:129]
	v_add_f32_e32 v234, v234, v235
	v_fmamk_f32 v234, v234, 0x3a800000, v229
	v_rsq_f32_e32 v148, v234
	ds_read_b128 v[234:237], v154 offset:768
	v_pk_mul_f32 v[128:129], v[128:129], s[68:69] op_sel_hi:[1,0]
	v_pk_mul_f32 v[126:127], v[126:127], v[150:151] op_sel_hi:[1,0]
	v_exp_f32_e32 v128, v128
	v_exp_f32_e32 v129, v129
	s_waitcnt lgkmcnt(1)
	v_mov_b32_e32 v152, v97
	v_mov_b32_e32 v153, v98
	v_mov_b32_e32 v97, v99
	v_pk_add_f32 v[96:97], v[152:153], v[96:97]
	v_pk_add_f32 v[128:129], v[128:129], 1.0 op_sel_hi:[1,0]
	v_add_f32_e32 v96, v96, v97
	v_fmamk_f32 v96, v96, 0x3a800000, v229
	v_rsq_f32_e32 v146, v96
	ds_read_b128 v[96:99], v154 offset:2048
	v_rcp_f32_e32 v128, v128
	v_rcp_f32_e32 v129, v129
	v_pk_mul_f32 v[120:121], v[120:121], v[150:151] op_sel_hi:[1,0]
	v_pk_mul_f32 v[116:117], v[116:117], v[150:151] op_sel_hi:[1,0]
	s_waitcnt lgkmcnt(1)
	v_mov_b32_e32 v152, v235
	v_mov_b32_e32 v153, v236
	v_mov_b32_e32 v235, v237
	v_pk_add_f32 v[234:235], v[152:153], v[234:235]
	v_pk_mul_f32 v[124:125], v[124:125], v[128:129]
	v_add_f32_e32 v234, v234, v235
	v_fmamk_f32 v234, v234, 0x3a800000, v229
	v_rsq_f32_e32 v144, v234
	ds_read_b128 v[234:237], v154 offset:2304
	v_pk_mul_f32 v[128:129], v[130:131], v[150:151] op_sel_hi:[1,0]
	v_pk_mul_f32 v[116:117], v[120:121], v[116:117]
	v_pk_mul_f32 v[126:127], v[128:129], v[126:127]
	v_pk_mul_f32 v[128:129], v[128:129], s[68:69] op_sel_hi:[1,0]
	s_waitcnt lgkmcnt(1)
	v_mov_b32_e32 v152, v97
	v_mov_b32_e32 v153, v98
	v_mov_b32_e32 v97, v99
	v_pk_add_f32 v[96:97], v[152:153], v[96:97]
	v_pk_mul_f32 v[120:121], v[120:121], s[68:69] op_sel_hi:[1,0]
	v_add_f32_e32 v96, v96, v97
	v_fmamk_f32 v96, v96, 0x3a800000, v229
	v_rsq_f32_e32 v142, v96
	ds_read_b128 v[96:99], v154 offset:2560
	v_exp_f32_e32 v128, v128
	v_exp_f32_e32 v129, v129
	v_exp_f32_e32 v120, v120
	v_exp_f32_e32 v121, v121
	s_waitcnt lgkmcnt(1)
	v_mov_b32_e32 v152, v235
	v_mov_b32_e32 v153, v236
	v_mov_b32_e32 v235, v237
	v_pk_add_f32 v[234:235], v[152:153], v[234:235]
	v_pk_mul_f32 v[112:113], v[112:113], v[148:149] op_sel_hi:[1,0]
	v_add_f32_e32 v234, v234, v235
	v_fmamk_f32 v234, v234, 0x3a800000, v229
	v_rsq_f32_e32 v140, v234
	ds_read_b128 v[234:237], v154 offset:2816
	v_pk_mul_f32 v[108:109], v[108:109], v[148:149] op_sel_hi:[1,0]
	v_pk_add_f32 v[128:129], v[128:129], 1.0 op_sel_hi:[1,0]
	v_pk_mul_f32 v[108:109], v[108:109], v[112:113]
	v_pk_mul_f32 v[112:113], v[112:113], s[68:69] op_sel_hi:[1,0]
	v_pk_add_f32 v[120:121], v[120:121], 1.0 op_sel_hi:[1,0]
	v_exp_f32_e32 v112, v112
	v_exp_f32_e32 v113, v113
	v_rcp_f32_e32 v128, v128
	v_rcp_f32_e32 v129, v129
	v_rcp_f32_e32 v120, v120
	v_rcp_f32_e32 v121, v121
	s_waitcnt lgkmcnt(1)
	v_mov_b32_e32 v152, v97
	v_mov_b32_e32 v153, v98
	v_mov_b32_e32 v97, v99
	v_pk_add_f32 v[96:97], v[152:153], v[96:97]
	v_pk_add_f32 v[112:113], v[112:113], 1.0 op_sel_hi:[1,0]
	v_add_f32_e32 v96, v96, v97
	v_fmamk_f32 v96, v96, 0x3a800000, v229
	v_pk_mul_f32 v[126:127], v[126:127], v[128:129]
	v_pk_mul_f32 v[116:117], v[116:117], v[120:121]
	v_rcp_f32_e32 v112, v112
	v_rcp_f32_e32 v113, v113
	v_rsq_f32_e32 v138, v96
	v_cvt_pk_bf16_f32 v124, v124, v125
	v_cvt_pk_bf16_f32 v125, v126, v127
	v_cvt_pk_bf16_f32 v126, v116, v117
	v_pk_mul_f32 v[116:117], v[122:123], v[150:151] op_sel_hi:[1,0]
	v_pk_mul_f32 v[118:119], v[118:119], v[150:151] op_sel_hi:[1,0]
	v_pk_mul_f32 v[108:109], v[108:109], v[112:113]
	v_pk_mul_f32 v[118:119], v[116:117], v[118:119]
	v_pk_mul_f32 v[116:117], v[116:117], s[68:69] op_sel_hi:[1,0]
	v_pk_mul_f32 v[112:113], v[114:115], v[148:149] op_sel_hi:[1,0]
	v_exp_f32_e32 v116, v116
	v_exp_f32_e32 v117, v117
	v_pk_mul_f32 v[110:111], v[110:111], v[148:149] op_sel_hi:[1,0]
	v_pk_mul_f32 v[104:105], v[104:105], v[148:149] op_sel_hi:[1,0]
	v_pk_mul_f32 v[100:101], v[100:101], v[148:149] op_sel_hi:[1,0]
	v_pk_mul_f32 v[110:111], v[112:113], v[110:111]
	v_pk_mul_f32 v[112:113], v[112:113], s[68:69] op_sel_hi:[1,0]
	v_pk_mul_f32 v[100:101], v[104:105], v[100:101]
	v_pk_mul_f32 v[104:105], v[104:105], s[68:69] op_sel_hi:[1,0]
	v_exp_f32_e32 v112, v112
	v_exp_f32_e32 v113, v113
	v_exp_f32_e32 v104, v104
	v_exp_f32_e32 v105, v105
	v_pk_add_f32 v[116:117], v[116:117], 1.0 op_sel_hi:[1,0]
	v_pk_mul_f32 v[92:93], v[92:93], v[146:147] op_sel_hi:[1,0]
	v_rcp_f32_e32 v116, v116
	v_rcp_f32_e32 v117, v117
	v_pk_mul_f32 v[88:89], v[88:89], v[146:147] op_sel_hi:[1,0]
	v_pk_add_f32 v[112:113], v[112:113], 1.0 op_sel_hi:[1,0]
	v_pk_mul_f32 v[88:89], v[88:89], v[92:93]
	v_pk_mul_f32 v[92:93], v[92:93], s[68:69] op_sel_hi:[1,0]
	v_pk_add_f32 v[104:105], v[104:105], 1.0 op_sel_hi:[1,0]
	v_exp_f32_e32 v92, v92
	v_exp_f32_e32 v93, v93
	v_rcp_f32_e32 v112, v112
	v_rcp_f32_e32 v113, v113
	v_rcp_f32_e32 v104, v104
	v_rcp_f32_e32 v105, v105
	v_lshl_or_b32 v152, s1, 7, v147
	v_pk_mul_f32 v[116:117], v[118:119], v[116:117]
	v_ashrrev_i32_e32 v153, 31, v152
	v_cvt_pk_bf16_f32 v127, v116, v117
	v_mov_b64_e32 v[116:117], s[8:9]
	v_mad_i64_i32 v[120:121], s[0:1], v151, s42, v[116:117]
	v_lshlrev_b64 v[118:119], 1, v[152:153]
	v_pk_add_f32 v[92:93], v[92:93], 1.0 op_sel_hi:[1,0]
	v_lshl_add_u64 v[120:121], v[120:121], 0, v[118:119]
	v_pk_mul_f32 v[110:111], v[110:111], v[112:113]
	v_pk_mul_f32 v[100:101], v[100:101], v[104:105]
	v_rcp_f32_e32 v92, v92
	v_rcp_f32_e32 v93, v93
	global_store_dwordx4 v[120:121], v[124:127], off sc1
	v_cvt_pk_bf16_f32 v108, v108, v109
	v_cvt_pk_bf16_f32 v109, v110, v111
	v_cvt_pk_bf16_f32 v110, v100, v101
	v_pk_mul_f32 v[100:101], v[106:107], v[148:149] op_sel_hi:[1,0]
	v_pk_mul_f32 v[102:103], v[102:103], v[148:149] op_sel_hi:[1,0]
	v_pk_mul_f32 v[88:89], v[88:89], v[92:93]
	v_pk_mul_f32 v[102:103], v[100:101], v[102:103]
	v_pk_mul_f32 v[100:101], v[100:101], s[68:69] op_sel_hi:[1,0]
	v_pk_mul_f32 v[92:93], v[94:95], v[146:147] op_sel_hi:[1,0]
	v_exp_f32_e32 v100, v100
	v_exp_f32_e32 v101, v101
	v_pk_mul_f32 v[90:91], v[90:91], v[146:147] op_sel_hi:[1,0]
	v_pk_mul_f32 v[84:85], v[84:85], v[146:147] op_sel_hi:[1,0]
	v_pk_mul_f32 v[80:81], v[80:81], v[146:147] op_sel_hi:[1,0]
	v_pk_mul_f32 v[90:91], v[92:93], v[90:91]
	v_pk_mul_f32 v[92:93], v[92:93], s[68:69] op_sel_hi:[1,0]
	v_pk_mul_f32 v[80:81], v[84:85], v[80:81]
	v_pk_mul_f32 v[84:85], v[84:85], s[68:69] op_sel_hi:[1,0]
	v_exp_f32_e32 v92, v92
	v_exp_f32_e32 v93, v93
	v_exp_f32_e32 v84, v84
	v_exp_f32_e32 v85, v85
	v_pk_add_f32 v[100:101], v[100:101], 1.0 op_sel_hi:[1,0]
	v_pk_mul_f32 v[76:77], v[76:77], v[144:145] op_sel_hi:[1,0]
	v_rcp_f32_e32 v100, v100
	v_rcp_f32_e32 v101, v101
	v_pk_mul_f32 v[72:73], v[72:73], v[144:145] op_sel_hi:[1,0]
	v_pk_add_f32 v[92:93], v[92:93], 1.0 op_sel_hi:[1,0]
	v_pk_mul_f32 v[72:73], v[72:73], v[76:77]
	v_pk_mul_f32 v[76:77], v[76:77], s[68:69] op_sel_hi:[1,0]
	v_pk_add_f32 v[84:85], v[84:85], 1.0 op_sel_hi:[1,0]
	v_exp_f32_e32 v76, v76
	v_exp_f32_e32 v77, v77
	v_rcp_f32_e32 v92, v92
	v_rcp_f32_e32 v93, v93
	v_rcp_f32_e32 v84, v84
	v_rcp_f32_e32 v85, v85
	v_pk_mul_f32 v[100:101], v[102:103], v[100:101]
	v_pk_add_f32 v[76:77], v[76:77], 1.0 op_sel_hi:[1,0]
	v_cvt_pk_bf16_f32 v111, v100, v101
	v_or_b32_e32 v100, 16, v151
	v_mad_i64_i32 v[100:101], s[0:1], v100, s42, v[116:117]
	v_lshl_add_u64 v[100:101], v[100:101], 0, v[118:119]
	v_pk_mul_f32 v[90:91], v[90:91], v[92:93]
	v_pk_mul_f32 v[80:81], v[80:81], v[84:85]
	v_rcp_f32_e32 v76, v76
	v_rcp_f32_e32 v77, v77
	global_store_dwordx4 v[100:101], v[108:111], off sc1
	v_cvt_pk_bf16_f32 v88, v88, v89
	v_cvt_pk_bf16_f32 v89, v90, v91
	v_cvt_pk_bf16_f32 v90, v80, v81
	v_pk_mul_f32 v[80:81], v[86:87], v[146:147] op_sel_hi:[1,0]
	v_pk_mul_f32 v[82:83], v[82:83], v[146:147] op_sel_hi:[1,0]
	v_pk_mul_f32 v[72:73], v[72:73], v[76:77]
	v_pk_mul_f32 v[82:83], v[80:81], v[82:83]
	v_pk_mul_f32 v[80:81], v[80:81], s[68:69] op_sel_hi:[1,0]
	v_pk_mul_f32 v[76:77], v[78:79], v[144:145] op_sel_hi:[1,0]
	v_exp_f32_e32 v80, v80
	v_exp_f32_e32 v81, v81
	v_pk_mul_f32 v[74:75], v[74:75], v[144:145] op_sel_hi:[1,0]
	v_pk_mul_f32 v[68:69], v[68:69], v[144:145] op_sel_hi:[1,0]
	v_pk_mul_f32 v[64:65], v[64:65], v[144:145] op_sel_hi:[1,0]
	v_pk_mul_f32 v[74:75], v[76:77], v[74:75]
	v_pk_mul_f32 v[76:77], v[76:77], s[68:69] op_sel_hi:[1,0]
	v_pk_mul_f32 v[64:65], v[68:69], v[64:65]
	v_pk_mul_f32 v[68:69], v[68:69], s[68:69] op_sel_hi:[1,0]
	v_exp_f32_e32 v76, v76
	v_exp_f32_e32 v77, v77
	v_exp_f32_e32 v68, v68
	v_exp_f32_e32 v69, v69
	v_pk_add_f32 v[80:81], v[80:81], 1.0 op_sel_hi:[1,0]
	v_pk_add_f32 v[76:77], v[76:77], 1.0 op_sel_hi:[1,0]
	v_rcp_f32_e32 v80, v80
	v_rcp_f32_e32 v81, v81
	v_pk_add_f32 v[68:69], v[68:69], 1.0 op_sel_hi:[1,0]
	v_rcp_f32_e32 v76, v76
	v_rcp_f32_e32 v77, v77
	v_rcp_f32_e32 v68, v68
	v_rcp_f32_e32 v69, v69
	v_pk_mul_f32 v[80:81], v[82:83], v[80:81]
	v_pk_mul_f32 v[74:75], v[74:75], v[76:77]
	v_cvt_pk_bf16_f32 v91, v80, v81
	v_or_b32_e32 v80, 32, v151
	v_mad_i64_i32 v[80:81], s[0:1], v80, s42, v[116:117]
	v_lshl_add_u64 v[80:81], v[80:81], 0, v[118:119]
	v_pk_mul_f32 v[64:65], v[64:65], v[68:69]
	global_store_dwordx4 v[80:81], v[88:91], off sc1
	v_cvt_pk_bf16_f32 v72, v72, v73
	v_cvt_pk_bf16_f32 v73, v74, v75
	v_cvt_pk_bf16_f32 v74, v64, v65
	v_pk_mul_f32 v[64:65], v[70:71], v[144:145] op_sel_hi:[1,0]
	v_pk_mul_f32 v[66:67], v[66:67], v[144:145] op_sel_hi:[1,0]
	s_nop 0
	v_pk_mul_f32 v[66:67], v[64:65], v[66:67]
	v_pk_mul_f32 v[64:65], v[64:65], s[68:69] op_sel_hi:[1,0]
	s_nop 0
	v_exp_f32_e32 v64, v64
	v_exp_f32_e32 v65, v65
	s_nop 0
	v_pk_add_f32 v[64:65], v[64:65], 1.0 op_sel_hi:[1,0]
	s_nop 0
	v_rcp_f32_e32 v64, v64
	v_rcp_f32_e32 v65, v65
	s_nop 0
	v_pk_mul_f32 v[64:65], v[66:67], v[64:65]
	s_nop 0
	v_cvt_pk_bf16_f32 v75, v64, v65
	v_or_b32_e32 v64, 48, v151
	v_mad_i64_i32 v[64:65], s[0:1], v64, s42, v[116:117]
	v_lshl_add_u64 v[64:65], v[64:65], 0, v[118:119]
	global_store_dwordx4 v[64:65], v[72:75], off sc1
	v_add_u32_e32 v64, 0x80, v151
	v_pk_mul_f32 v[60:61], v[60:61], v[142:143] op_sel_hi:[1,0]
	v_pk_mul_f32 v[56:57], v[56:57], v[142:143] op_sel_hi:[1,0]
	v_pk_mul_f32 v[58:59], v[58:59], v[142:143] op_sel_hi:[1,0]
	v_pk_mul_f32 v[56:57], v[60:61], v[56:57]
	v_pk_mul_f32 v[60:61], v[60:61], s[68:69] op_sel_hi:[1,0]
	v_pk_mul_f32 v[52:53], v[52:53], v[142:143] op_sel_hi:[1,0]
	v_exp_f32_e32 v60, v60
	v_exp_f32_e32 v61, v61
	v_pk_mul_f32 v[48:49], v[48:49], v[142:143] op_sel_hi:[1,0]
	v_pk_mul_f32 v[44:45], v[44:45], v[140:141] op_sel_hi:[1,0]
	v_pk_mul_f32 v[48:49], v[52:53], v[48:49]
	v_pk_add_f32 v[60:61], v[60:61], 1.0 op_sel_hi:[1,0]
	v_pk_mul_f32 v[52:53], v[52:53], s[68:69] op_sel_hi:[1,0]
	v_rcp_f32_e32 v60, v60
	v_rcp_f32_e32 v61, v61
	v_exp_f32_e32 v52, v52
	v_exp_f32_e32 v53, v53
	v_pk_mul_f32 v[40:41], v[40:41], v[140:141] op_sel_hi:[1,0]
	v_pk_mul_f32 v[56:57], v[56:57], v[60:61]
	v_pk_mul_f32 v[60:61], v[62:63], v[142:143] op_sel_hi:[1,0]
	v_pk_mul_f32 v[40:41], v[40:41], v[44:45]
	v_pk_mul_f32 v[58:59], v[60:61], v[58:59]
	v_pk_mul_f32 v[60:61], v[60:61], s[68:69] op_sel_hi:[1,0]
	v_pk_mul_f32 v[44:45], v[44:45], s[68:69] op_sel_hi:[1,0]
	v_exp_f32_e32 v60, v60
	v_exp_f32_e32 v61, v61
	v_exp_f32_e32 v44, v44
	v_exp_f32_e32 v45, v45
	v_pk_add_f32 v[52:53], v[52:53], 1.0 op_sel_hi:[1,0]
	v_pk_add_f32 v[60:61], v[60:61], 1.0 op_sel_hi:[1,0]
	v_rcp_f32_e32 v52, v52
	v_rcp_f32_e32 v60, v60
	v_rcp_f32_e32 v61, v61
	v_rcp_f32_e32 v53, v53
	v_pk_add_f32 v[44:45], v[44:45], 1.0 op_sel_hi:[1,0]
	v_cvt_pk_bf16_f32 v56, v56, v57
	v_pk_mul_f32 v[58:59], v[58:59], v[60:61]
	v_rcp_f32_e32 v44, v44
	v_rcp_f32_e32 v45, v45
	v_pk_mul_f32 v[48:49], v[48:49], v[52:53]
	v_cvt_pk_bf16_f32 v57, v58, v59
	v_pk_mul_f32 v[50:51], v[50:51], v[142:143] op_sel_hi:[1,0]
	v_cvt_pk_bf16_f32 v58, v48, v49
	v_pk_mul_f32 v[48:49], v[54:55], v[142:143] op_sel_hi:[1,0]
	v_pk_mul_f32 v[40:41], v[40:41], v[44:45]
	v_pk_mul_f32 v[50:51], v[48:49], v[50:51]
	v_pk_mul_f32 v[48:49], v[48:49], s[68:69] op_sel_hi:[1,0]
	v_pk_mul_f32 v[44:45], v[46:47], v[140:141] op_sel_hi:[1,0]
	v_exp_f32_e32 v48, v48
	v_exp_f32_e32 v49, v49
	v_pk_mul_f32 v[42:43], v[42:43], v[140:141] op_sel_hi:[1,0]
	v_pk_mul_f32 v[36:37], v[36:37], v[140:141] op_sel_hi:[1,0]
	v_pk_mul_f32 v[32:33], v[32:33], v[140:141] op_sel_hi:[1,0]
	v_pk_mul_f32 v[42:43], v[44:45], v[42:43]
	v_pk_mul_f32 v[44:45], v[44:45], s[68:69] op_sel_hi:[1,0]
	v_pk_mul_f32 v[32:33], v[36:37], v[32:33]
	v_pk_mul_f32 v[36:37], v[36:37], s[68:69] op_sel_hi:[1,0]
	v_exp_f32_e32 v44, v44
	v_exp_f32_e32 v45, v45
	v_exp_f32_e32 v36, v36
	v_exp_f32_e32 v37, v37
	v_pk_add_f32 v[48:49], v[48:49], 1.0 op_sel_hi:[1,0]
	v_pk_mul_f32 v[28:29], v[28:29], v[138:139] op_sel_hi:[1,0]
	v_pk_mul_f32 v[24:25], v[24:25], v[138:139] op_sel_hi:[1,0]
	v_rcp_f32_e32 v48, v48
	v_rcp_f32_e32 v49, v49
	v_pk_mul_f32 v[24:25], v[24:25], v[28:29]
	v_pk_mul_f32 v[28:29], v[28:29], s[68:69] op_sel_hi:[1,0]
	v_pk_add_f32 v[44:45], v[44:45], 1.0 op_sel_hi:[1,0]
	v_pk_add_f32 v[36:37], v[36:37], 1.0 op_sel_hi:[1,0]
	v_exp_f32_e32 v28, v28
	v_exp_f32_e32 v29, v29
	v_rcp_f32_e32 v44, v44
	v_rcp_f32_e32 v45, v45
	v_rcp_f32_e32 v36, v36
	v_rcp_f32_e32 v37, v37
	v_pk_mul_f32 v[48:49], v[50:51], v[48:49]
	v_pk_add_f32 v[28:29], v[28:29], 1.0 op_sel_hi:[1,0]
	v_cvt_pk_bf16_f32 v59, v48, v49
	v_mad_i64_i32 v[48:49], s[0:1], v64, s42, v[116:117]
	v_lshl_add_u64 v[48:49], v[48:49], 0, v[118:119]
	v_pk_mul_f32 v[42:43], v[42:43], v[44:45]
	v_pk_mul_f32 v[32:33], v[32:33], v[36:37]
	v_rcp_f32_e32 v28, v28
	v_rcp_f32_e32 v29, v29
	global_store_dwordx4 v[48:49], v[56:59], off sc1
	v_cvt_pk_bf16_f32 v40, v40, v41
	v_cvt_pk_bf16_f32 v41, v42, v43
	v_cvt_pk_bf16_f32 v42, v32, v33
	v_pk_mul_f32 v[32:33], v[38:39], v[140:141] op_sel_hi:[1,0]
	v_pk_mul_f32 v[34:35], v[34:35], v[140:141] op_sel_hi:[1,0]
	v_pk_mul_f32 v[24:25], v[24:25], v[28:29]
	v_pk_mul_f32 v[34:35], v[32:33], v[34:35]
	v_pk_mul_f32 v[32:33], v[32:33], s[68:69] op_sel_hi:[1,0]
	v_pk_mul_f32 v[28:29], v[30:31], v[138:139] op_sel_hi:[1,0]
	v_exp_f32_e32 v32, v32
	v_exp_f32_e32 v33, v33
	v_pk_mul_f32 v[26:27], v[26:27], v[138:139] op_sel_hi:[1,0]
	v_pk_mul_f32 v[20:21], v[20:21], v[138:139] op_sel_hi:[1,0]
	v_pk_mul_f32 v[16:17], v[16:17], v[138:139] op_sel_hi:[1,0]
	v_pk_mul_f32 v[26:27], v[28:29], v[26:27]
	v_pk_mul_f32 v[28:29], v[28:29], s[68:69] op_sel_hi:[1,0]
	v_pk_mul_f32 v[16:17], v[20:21], v[16:17]
	v_pk_mul_f32 v[20:21], v[20:21], s[68:69] op_sel_hi:[1,0]
	v_exp_f32_e32 v28, v28
	v_exp_f32_e32 v29, v29
	v_exp_f32_e32 v20, v20
	v_exp_f32_e32 v21, v21
	v_pk_add_f32 v[32:33], v[32:33], 1.0 op_sel_hi:[1,0]
	v_pk_add_f32 v[28:29], v[28:29], 1.0 op_sel_hi:[1,0]
	v_rcp_f32_e32 v32, v32
	v_rcp_f32_e32 v33, v33
	v_pk_add_f32 v[20:21], v[20:21], 1.0 op_sel_hi:[1,0]
	v_rcp_f32_e32 v28, v28
	v_rcp_f32_e32 v29, v29
	v_rcp_f32_e32 v20, v20
	v_rcp_f32_e32 v21, v21
	v_pk_mul_f32 v[32:33], v[34:35], v[32:33]
	v_pk_mul_f32 v[26:27], v[26:27], v[28:29]
	v_cvt_pk_bf16_f32 v43, v32, v33
	v_add_u32_e32 v32, 0x90, v151
	v_mad_i64_i32 v[32:33], s[0:1], v32, s42, v[116:117]
	v_lshl_add_u64 v[32:33], v[32:33], 0, v[118:119]
	v_pk_mul_f32 v[16:17], v[16:17], v[20:21]
	global_store_dwordx4 v[32:33], v[40:43], off sc1
	v_cvt_pk_bf16_f32 v24, v24, v25
	v_cvt_pk_bf16_f32 v25, v26, v27
	v_cvt_pk_bf16_f32 v26, v16, v17
	v_pk_mul_f32 v[16:17], v[22:23], v[138:139] op_sel_hi:[1,0]
	v_pk_mul_f32 v[18:19], v[18:19], v[138:139] op_sel_hi:[1,0]
	s_mov_b64 s[24:25], -1
	v_pk_mul_f32 v[18:19], v[16:17], v[18:19]
	v_pk_mul_f32 v[16:17], v[16:17], s[68:69] op_sel_hi:[1,0]
	s_andn2_b64 vcc, exec, s[4:5]
	v_exp_f32_e32 v16, v16
	v_exp_f32_e32 v17, v17
	s_nop 0
	v_pk_add_f32 v[16:17], v[16:17], 1.0 op_sel_hi:[1,0]
	s_nop 0
	v_rcp_f32_e32 v16, v16
	v_rcp_f32_e32 v17, v17
	s_nop 0
	v_pk_mul_f32 v[16:17], v[18:19], v[16:17]
	s_nop 0
	v_cvt_pk_bf16_f32 v27, v16, v17
	v_add_u32_e32 v16, 0xa0, v151
	v_mad_i64_i32 v[16:17], s[0:1], v16, s42, v[116:117]
	v_lshl_add_u64 v[16:17], v[16:17], 0, v[118:119]
	global_store_dwordx4 v[16:17], v[24:27], off sc1
	s_waitcnt lgkmcnt(0)
	v_mov_b32_e32 v16, v235
	v_mov_b32_e32 v17, v236
	v_mov_b32_e32 v235, v237
	v_pk_add_f32 v[16:17], v[16:17], v[234:235]
	s_nop 0
	v_add_f32_e32 v16, v16, v17
	v_fmamk_f32 v16, v16, 0x3a800000, v229
	v_rsq_f32_e32 v16, v16
	s_nop 0
	v_pk_mul_f32 v[12:13], v[12:13], v[16:17] op_sel_hi:[1,0]
	v_pk_mul_f32 v[8:9], v[8:9], v[16:17] op_sel_hi:[1,0]
	v_pk_mul_f32 v[10:11], v[10:11], v[16:17] op_sel_hi:[1,0]
	v_pk_mul_f32 v[8:9], v[8:9], v[12:13]
	v_pk_mul_f32 v[12:13], v[12:13], s[68:69] op_sel_hi:[1,0]
	v_pk_mul_f32 v[4:5], v[4:5], v[16:17] op_sel_hi:[1,0]
	v_exp_f32_e32 v12, v12
	v_exp_f32_e32 v13, v13
	v_pk_mul_f32 v[0:1], v[0:1], v[16:17] op_sel_hi:[1,0]
	v_pk_mul_f32 v[2:3], v[2:3], v[16:17] op_sel_hi:[1,0]
	v_pk_mul_f32 v[0:1], v[4:5], v[0:1]
	v_pk_add_f32 v[12:13], v[12:13], 1.0 op_sel_hi:[1,0]
	v_pk_mul_f32 v[4:5], v[4:5], s[68:69] op_sel_hi:[1,0]
	v_rcp_f32_e32 v12, v12
	v_rcp_f32_e32 v13, v13
	v_exp_f32_e32 v4, v4
	v_exp_f32_e32 v5, v5
	v_pk_mul_f32 v[8:9], v[8:9], v[12:13]
	v_pk_mul_f32 v[12:13], v[14:15], v[16:17] op_sel_hi:[1,0]
	v_pk_add_f32 v[4:5], v[4:5], 1.0 op_sel_hi:[1,0]
	v_pk_mul_f32 v[10:11], v[12:13], v[10:11]
	v_pk_mul_f32 v[12:13], v[12:13], s[68:69] op_sel_hi:[1,0]
	v_rcp_f32_e32 v4, v4
	v_exp_f32_e32 v12, v12
	v_exp_f32_e32 v13, v13
	v_rcp_f32_e32 v5, v5
	v_cvt_pk_bf16_f32 v8, v8, v9
	v_pk_add_f32 v[12:13], v[12:13], 1.0 op_sel_hi:[1,0]
	s_nop 0
	v_rcp_f32_e32 v12, v12
	v_rcp_f32_e32 v13, v13
	v_pk_mul_f32 v[0:1], v[0:1], v[4:5]
	v_pk_mul_f32 v[10:11], v[10:11], v[12:13]
	s_nop 0
	v_cvt_pk_bf16_f32 v9, v10, v11
	v_cvt_pk_bf16_f32 v10, v0, v1
	v_pk_mul_f32 v[0:1], v[6:7], v[16:17] op_sel_hi:[1,0]
	s_nop 0
	v_pk_mul_f32 v[2:3], v[0:1], v[2:3]
	v_pk_mul_f32 v[0:1], v[0:1], s[68:69] op_sel_hi:[1,0]
	s_nop 0
	v_exp_f32_e32 v0, v0
	v_exp_f32_e32 v1, v1
	s_nop 0
	v_pk_add_f32 v[0:1], v[0:1], 1.0 op_sel_hi:[1,0]
	s_nop 0
	v_rcp_f32_e32 v0, v0
	v_rcp_f32_e32 v1, v1
	s_nop 0
	v_pk_mul_f32 v[0:1], v[2:3], v[0:1]
	s_nop 0
	v_cvt_pk_bf16_f32 v11, v0, v1
	v_add_u32_e32 v0, 0xb0, v151
	v_mad_i64_i32 v[0:1], s[0:1], v0, s42, v[116:117]
	v_lshl_add_u64 v[0:1], v[0:1], 0, v[118:119]
	global_store_dwordx4 v[0:1], v[8:11], off sc1
	s_cbranch_vccnz .LBB0_522
	s_andn2_b64 vcc, exec, s[6:7]
	s_cbranch_vccnz .LBB0_521
	s_barrier
	s_branch .LBB0_521
